# down-projection fused-norm epilogue: the four g_final loads issued before the row-statistics poll (into the dead gate registers)
# baseline (speedup 1.0000x reference)
;     static __device__ __forceinline__ f32x4 ldb(const void* base, size_t idx) { if (MODE == 0) return *(const f32x4*)((const float*)base + idx); const u32x2 w = *(const u32x2*)((const bf16_t*)base + idx); return (f32x4){bflo(w.x), bfhi(w.x), bflo(w.y), bfhi(w.y)}; }
;     __device__ __forceinline__ void operator()(const f32x4 (&acc)[2][2][4][2], const Unit& u, int wr, int wc, int fr, int fq) const {
;     ...
;         const float* gp0 = gate + (size_t)((u.pm * BM) >> 11) * NMOD + col0;
;         f32x4 gt[2][2];
; #pragma unroll
;         for (int bj = 0; bj < 2; ++bj)
; #pragma unroll
;             for (int n = 0; n < 2; ++n) gt[bj][n] = *(const f32x4*)(gp0 + bj * HALF + n * 16);
; #pragma unroll
;         for (int ai = 0; ai < 2; ++ai)
; #pragma unroll
;           for (int mp = 0; mp < 2; ++mp) { f32x4 bb[2][2][2];
; #pragma unroll
;             for (int mm = 0; mm < 2; ++mm) { const size_t bi = (size_t)(row0 + ai * HALF + (2 * mp + mm) * 16) * DM + col0;
; #pragma unroll
;                 for (int bj = 0; bj < 2; ++bj)
; #pragma unroll
;                     for (int n = 0; n < 2; ++n) bb[mm][bj][n] = ldb(baseP, bi + bj * HALF + n * 16); }
; #pragma unroll
;             for (int mm = 0; mm < 2; ++mm) { const int m = 2 * mp + mm; float s = 0.f;
; #pragma unroll
;                 for (int bj = 0; bj < 2; ++bj)
; #pragma unroll
;                     for (int n = 0; n < 2; ++n) { const f32x4 x = bb[mm][bj][n] + gt[bj][n] * acc[ai][bj][m][n]; s += (x[0] * x[0] + x[1] * x[1]) + (x[2] * x[2] + x[3] * x[3]); }
;                 s += __shfl_xor(s, 16); s += __shfl_xor(s, 32);
;                 if (fq == 0) P[(ai * HALF + wr * 64 + m * 16 + fr) * 4 + wc] = s; }
.LBB0_1602:
	s_lshl_b32 s41, s14, 8
	v_mbcnt_lo_u32_b32 v156, -1, 0
	v_mbcnt_hi_u32_b32 v156, -1, v156
	s_add_i32 s8, s41, s29
	v_and_b32_e32 v190, 15, v156
	v_or_b32_e32 v174, s8, v190
	s_lshl_b32 s8, s68, 8
	v_readlane_b32 s9, v237, 10
	v_ashrrev_i32_e32 v191, 4, v156
	s_or_b32 s8, s8, s9
	v_lshl_add_u32 v176, v191, 2, s8
	s_mov_b64 s[12:13], -1
	s_cmp_lt_i32 s40, 0
	v_ashrrev_i32_e32 v177, 31, v176
	s_cbranch_scc0 .LBB0_1644
	v_ashrrev_i32_e32 v175, 31, v174
	s_ashr_i32 s8, s14, 3
	s_mul_hi_i32 s9, s8, 0x6000
	s_mulk_i32 s8, 0x6000
	s_add_u32 s12, s26, s8
	s_addc_u32 s13, s27, s9
	v_lshl_add_u64 v[146:147], v[176:177], 2, s[12:13]
	global_load_dwordx4 v[142:145], v[146:147], off
	global_load_dwordx4 v[138:141], v[146:147], off offset:64
	global_load_dwordx4 v[134:137], v[146:147], off offset:512
	global_load_dwordx4 v[130:133], v[146:147], off offset:576
	v_lshl_add_u64 v[146:147], v[176:177], 1, s[42:43]
	v_lshlrev_b64 v[148:149], 11, v[174:175]
	v_lshl_add_u64 v[148:149], v[146:147], 0, v[148:149]
	s_mov_b64 s[24:25], 0x8000
	s_mov_b64 s[70:71], 0x28000
	global_load_dwordx2 v[150:151], v[148:149], off
	global_load_dwordx2 v[152:153], v[148:149], off offset:32
	global_load_dwordx2 v[154:155], v[148:149], off offset:256
	global_load_dwordx2 v[158:159], v[148:149], off offset:288
	v_lshl_add_u64 v[148:149], v[148:149], 0, s[24:25]
	global_load_dwordx2 v[160:161], v[148:149], off
	global_load_dwordx2 v[178:179], v[148:149], off offset:32
	global_load_dwordx2 v[180:181], v[148:149], off offset:256
	global_load_dwordx2 v[192:193], v[148:149], off offset:288
	v_lshl_add_u64 v[148:149], v[148:149], 0, s[24:25]
	global_load_dwordx2 v[194:195], v[148:149], off
	global_load_dwordx2 v[196:197], v[148:149], off offset:32
	global_load_dwordx2 v[198:199], v[148:149], off offset:256
	global_load_dwordx2 v[200:201], v[148:149], off offset:288
	v_lshl_add_u64 v[148:149], v[148:149], 0, s[24:25]
	global_load_dwordx2 v[202:203], v[148:149], off
	global_load_dwordx2 v[204:205], v[148:149], off offset:32
	global_load_dwordx2 v[206:207], v[148:149], off offset:256
	global_load_dwordx2 v[210:211], v[148:149], off offset:288
	v_lshl_add_u64 v[148:149], v[148:149], 0, s[70:71]
	global_load_dwordx2 v[212:213], v[148:149], off
	global_load_dwordx2 v[214:215], v[148:149], off offset:32
	global_load_dwordx2 v[216:217], v[148:149], off offset:256
	global_load_dwordx2 v[218:219], v[148:149], off offset:288
	v_lshl_add_u64 v[148:149], v[148:149], 0, s[24:25]
	global_load_dwordx2 v[220:221], v[148:149], off
	global_load_dwordx2 v[222:223], v[148:149], off offset:32
	global_load_dwordx2 v[226:227], v[148:149], off offset:256
	global_load_dwordx2 v[228:229], v[148:149], off offset:288
	v_lshl_add_u64 v[148:149], v[148:149], 0, s[24:25]
	global_load_dwordx2 v[230:231], v[148:149], off
	global_load_dwordx2 v[232:233], v[148:149], off offset:32
	global_load_dwordx2 v[234:235], v[148:149], off offset:256
	global_load_dwordx2 v[238:239], v[148:149], off offset:288
	v_lshl_add_u64 v[148:149], v[148:149], 0, s[24:25]
	global_load_dwordx2 v[240:241], v[148:149], off
	global_load_dwordx2 v[242:243], v[148:149], off offset:32
	global_load_dwordx2 v[244:245], v[148:149], off offset:256
	global_load_dwordx2 v[246:247], v[148:149], off offset:288
	v_xor_b32_e32 v157, 16, v156
	v_xor_b32_e32 v175, 32, v156
	v_or_b32_e32 v183, s29, v190
	v_lshlrev_b32_e32 v157, 2, v157
	v_lshlrev_b32_e32 v175, 2, v175
	v_lshl_add_u32 v182, v183, 4, s96
	v_cmp_gt_u32_e64 s[12:13], 16, v156
	s_waitcnt vmcnt(28)
	v_lshlrev_b32_e32 v146, 16, v150
	v_and_b32_e32 v147, 0xffff0000, v150
	v_lshlrev_b32_e32 v150, 16, v151
	v_and_b32_e32 v151, 0xffff0000, v151
	v_pk_fma_f32 v[126:127], v[126:127], v[142:143], v[146:147]
	v_pk_fma_f32 v[128:129], v[128:129], v[144:145], v[150:151]
	v_pk_mul_f32 v[150:151], v[126:127], v[126:127]
	v_pk_fma_f32 v[150:151], v[128:129], v[128:129], v[150:151]
	v_lshlrev_b32_e32 v146, 16, v152
	v_and_b32_e32 v147, 0xffff0000, v152
	v_lshlrev_b32_e32 v152, 16, v153
	v_and_b32_e32 v153, 0xffff0000, v153
	v_pk_fma_f32 v[122:123], v[122:123], v[138:139], v[146:147]
	v_pk_fma_f32 v[124:125], v[124:125], v[140:141], v[152:153]
	v_pk_fma_f32 v[150:151], v[122:123], v[122:123], v[150:151]
	v_pk_fma_f32 v[150:151], v[124:125], v[124:125], v[150:151]
	v_lshlrev_b32_e32 v146, 16, v154
	v_and_b32_e32 v147, 0xffff0000, v154
	v_lshlrev_b32_e32 v154, 16, v155
	v_and_b32_e32 v155, 0xffff0000, v155
	v_pk_fma_f32 v[110:111], v[110:111], v[134:135], v[146:147]
	v_pk_fma_f32 v[112:113], v[112:113], v[136:137], v[154:155]
	v_pk_fma_f32 v[150:151], v[110:111], v[110:111], v[150:151]
	v_pk_fma_f32 v[150:151], v[112:113], v[112:113], v[150:151]
	v_lshlrev_b32_e32 v146, 16, v158
	v_and_b32_e32 v147, 0xffff0000, v158
	v_lshlrev_b32_e32 v158, 16, v159
	v_and_b32_e32 v159, 0xffff0000, v159
	v_pk_fma_f32 v[102:103], v[102:103], v[130:131], v[146:147]
	v_pk_fma_f32 v[104:105], v[104:105], v[132:133], v[158:159]
	v_pk_fma_f32 v[150:151], v[102:103], v[102:103], v[150:151]
	v_pk_fma_f32 v[150:151], v[104:105], v[104:105], v[150:151]
	v_add_f32_e32 v150, v150, v151
	s_waitcnt vmcnt(24)
;     __device__ __forceinline__ void operator()(const f32x4 (&acc)[2][2][4][2], const Unit& u, int wr, int wc, int fr, int fq) const {
;     ...
;             for (int mm = 0; mm < 2; ++mm) { const int m = 2 * mp + mm; float s = 0.f;
; #pragma unroll
;                 for (int bj = 0; bj < 2; ++bj)
; #pragma unroll
;                     for (int n = 0; n < 2; ++n) { const f32x4 x = bb[mm][bj][n] + gt[bj][n] * acc[ai][bj][m][n]; s += (x[0] * x[0] + x[1] * x[1]) + (x[2] * x[2] + x[3] * x[3]); }
;                 s += __shfl_xor(s, 16); s += __shfl_xor(s, 32);
;                 if (fq == 0) P[(ai * HALF + wr * 64 + m * 16 + fr) * 4 + wc] = s; }
	v_lshlrev_b32_e32 v146, 16, v160
	v_and_b32_e32 v147, 0xffff0000, v160
	v_lshlrev_b32_e32 v160, 16, v161
	v_and_b32_e32 v161, 0xffff0000, v161
	v_pk_fma_f32 v[118:119], v[118:119], v[142:143], v[146:147]
	v_pk_fma_f32 v[120:121], v[120:121], v[144:145], v[160:161]
	v_pk_mul_f32 v[160:161], v[118:119], v[118:119]
	v_pk_fma_f32 v[160:161], v[120:121], v[120:121], v[160:161]
	v_lshlrev_b32_e32 v146, 16, v178
	v_and_b32_e32 v147, 0xffff0000, v178
	v_lshlrev_b32_e32 v178, 16, v179
	v_and_b32_e32 v179, 0xffff0000, v179
	v_pk_fma_f32 v[114:115], v[114:115], v[138:139], v[146:147]
	v_pk_fma_f32 v[116:117], v[116:117], v[140:141], v[178:179]
	v_pk_fma_f32 v[160:161], v[114:115], v[114:115], v[160:161]
	v_pk_fma_f32 v[160:161], v[116:117], v[116:117], v[160:161]
	v_lshlrev_b32_e32 v146, 16, v180
	v_and_b32_e32 v147, 0xffff0000, v180
	v_lshlrev_b32_e32 v180, 16, v181
	v_and_b32_e32 v181, 0xffff0000, v181
	v_pk_fma_f32 v[94:95], v[94:95], v[134:135], v[146:147]
	v_pk_fma_f32 v[96:97], v[96:97], v[136:137], v[180:181]
	v_pk_fma_f32 v[160:161], v[94:95], v[94:95], v[160:161]
	v_pk_fma_f32 v[160:161], v[96:97], v[96:97], v[160:161]
	v_lshlrev_b32_e32 v146, 16, v192
	v_and_b32_e32 v147, 0xffff0000, v192
	v_lshlrev_b32_e32 v192, 16, v193
	v_and_b32_e32 v193, 0xffff0000, v193
	v_pk_fma_f32 v[86:87], v[86:87], v[130:131], v[146:147]
	v_pk_fma_f32 v[88:89], v[88:89], v[132:133], v[192:193]
	v_pk_fma_f32 v[160:161], v[86:87], v[86:87], v[160:161]
	v_pk_fma_f32 v[160:161], v[88:89], v[88:89], v[160:161]
	v_add_f32_e32 v160, v160, v161
	s_waitcnt vmcnt(20)
	v_lshlrev_b32_e32 v146, 16, v194
	v_and_b32_e32 v147, 0xffff0000, v194
	v_lshlrev_b32_e32 v194, 16, v195
	v_and_b32_e32 v195, 0xffff0000, v195
	v_pk_fma_f32 v[106:107], v[106:107], v[142:143], v[146:147]
	v_pk_fma_f32 v[108:109], v[108:109], v[144:145], v[194:195]
	v_pk_mul_f32 v[194:195], v[106:107], v[106:107]
	v_pk_fma_f32 v[194:195], v[108:109], v[108:109], v[194:195]
	v_lshlrev_b32_e32 v146, 16, v196
	v_and_b32_e32 v147, 0xffff0000, v196
	v_lshlrev_b32_e32 v196, 16, v197
	v_and_b32_e32 v197, 0xffff0000, v197
	v_pk_fma_f32 v[98:99], v[98:99], v[138:139], v[146:147]
	v_pk_fma_f32 v[100:101], v[100:101], v[140:141], v[196:197]
	v_pk_fma_f32 v[194:195], v[98:99], v[98:99], v[194:195]
	v_pk_fma_f32 v[194:195], v[100:101], v[100:101], v[194:195]
	v_lshlrev_b32_e32 v146, 16, v198
	v_and_b32_e32 v147, 0xffff0000, v198
	v_lshlrev_b32_e32 v198, 16, v199
	v_and_b32_e32 v199, 0xffff0000, v199
	v_pk_fma_f32 v[78:79], v[78:79], v[134:135], v[146:147]
	v_pk_fma_f32 v[80:81], v[80:81], v[136:137], v[198:199]
	v_pk_fma_f32 v[194:195], v[78:79], v[78:79], v[194:195]
	v_pk_fma_f32 v[194:195], v[80:81], v[80:81], v[194:195]
	v_lshlrev_b32_e32 v146, 16, v200
	v_and_b32_e32 v147, 0xffff0000, v200
	v_lshlrev_b32_e32 v200, 16, v201
	v_and_b32_e32 v201, 0xffff0000, v201
	v_pk_fma_f32 v[74:75], v[74:75], v[130:131], v[146:147]
	v_pk_fma_f32 v[76:77], v[76:77], v[132:133], v[200:201]
	v_pk_fma_f32 v[194:195], v[74:75], v[74:75], v[194:195]
	v_pk_fma_f32 v[194:195], v[76:77], v[76:77], v[194:195]
	v_add_f32_e32 v194, v194, v195
	s_waitcnt vmcnt(16)
	v_lshlrev_b32_e32 v146, 16, v202
	v_and_b32_e32 v147, 0xffff0000, v202
	v_lshlrev_b32_e32 v202, 16, v203
	v_and_b32_e32 v203, 0xffff0000, v203
	v_pk_fma_f32 v[90:91], v[90:91], v[142:143], v[146:147]
	v_pk_fma_f32 v[92:93], v[92:93], v[144:145], v[202:203]
	v_pk_mul_f32 v[202:203], v[90:91], v[90:91]
	v_pk_fma_f32 v[202:203], v[92:93], v[92:93], v[202:203]
	v_lshlrev_b32_e32 v146, 16, v204
	v_and_b32_e32 v147, 0xffff0000, v204
	v_lshlrev_b32_e32 v204, 16, v205
	v_and_b32_e32 v205, 0xffff0000, v205
	v_pk_fma_f32 v[82:83], v[82:83], v[138:139], v[146:147]
	v_pk_fma_f32 v[84:85], v[84:85], v[140:141], v[204:205]
	v_pk_fma_f32 v[202:203], v[82:83], v[82:83], v[202:203]
	v_pk_fma_f32 v[202:203], v[84:85], v[84:85], v[202:203]
	v_lshlrev_b32_e32 v146, 16, v206
	v_and_b32_e32 v147, 0xffff0000, v206
	v_lshlrev_b32_e32 v206, 16, v207
	v_and_b32_e32 v207, 0xffff0000, v207
	v_pk_fma_f32 v[70:71], v[70:71], v[134:135], v[146:147]
	v_pk_fma_f32 v[72:73], v[72:73], v[136:137], v[206:207]
	v_pk_fma_f32 v[202:203], v[70:71], v[70:71], v[202:203]
	v_pk_fma_f32 v[202:203], v[72:73], v[72:73], v[202:203]
	v_lshlrev_b32_e32 v146, 16, v210
	v_and_b32_e32 v147, 0xffff0000, v210
	v_lshlrev_b32_e32 v210, 16, v211
	v_and_b32_e32 v211, 0xffff0000, v211
	v_pk_fma_f32 v[66:67], v[66:67], v[130:131], v[146:147]
	v_pk_fma_f32 v[68:69], v[68:69], v[132:133], v[210:211]
	v_pk_fma_f32 v[202:203], v[66:67], v[66:67], v[202:203]
	v_pk_fma_f32 v[202:203], v[68:69], v[68:69], v[202:203]
	v_add_f32_e32 v202, v202, v203
	s_waitcnt vmcnt(12)
	v_lshlrev_b32_e32 v146, 16, v212
	v_and_b32_e32 v147, 0xffff0000, v212
	v_lshlrev_b32_e32 v212, 16, v213
	v_and_b32_e32 v213, 0xffff0000, v213
	v_pk_fma_f32 v[62:63], v[62:63], v[142:143], v[146:147]
	v_pk_fma_f32 v[64:65], v[64:65], v[144:145], v[212:213]
	v_pk_mul_f32 v[212:213], v[62:63], v[62:63]
	v_pk_fma_f32 v[212:213], v[64:65], v[64:65], v[212:213]
	v_lshlrev_b32_e32 v146, 16, v214
	v_and_b32_e32 v147, 0xffff0000, v214
	v_lshlrev_b32_e32 v214, 16, v215
	v_and_b32_e32 v215, 0xffff0000, v215
	v_pk_fma_f32 v[58:59], v[58:59], v[138:139], v[146:147]
	v_pk_fma_f32 v[60:61], v[60:61], v[140:141], v[214:215]
	v_pk_fma_f32 v[212:213], v[58:59], v[58:59], v[212:213]
	v_pk_fma_f32 v[212:213], v[60:61], v[60:61], v[212:213]
	v_lshlrev_b32_e32 v146, 16, v216
	v_and_b32_e32 v147, 0xffff0000, v216
	v_lshlrev_b32_e32 v216, 16, v217
	v_and_b32_e32 v217, 0xffff0000, v217
	v_pk_fma_f32 v[46:47], v[46:47], v[134:135], v[146:147]
	v_pk_fma_f32 v[48:49], v[48:49], v[136:137], v[216:217]
	v_pk_fma_f32 v[212:213], v[46:47], v[46:47], v[212:213]
	v_pk_fma_f32 v[212:213], v[48:49], v[48:49], v[212:213]
	v_lshlrev_b32_e32 v146, 16, v218
	v_and_b32_e32 v147, 0xffff0000, v218
	v_lshlrev_b32_e32 v218, 16, v219
	v_and_b32_e32 v219, 0xffff0000, v219
	v_pk_fma_f32 v[38:39], v[38:39], v[130:131], v[146:147]
	v_pk_fma_f32 v[40:41], v[40:41], v[132:133], v[218:219]
	v_pk_fma_f32 v[212:213], v[38:39], v[38:39], v[212:213]
	v_pk_fma_f32 v[212:213], v[40:41], v[40:41], v[212:213]
	v_add_f32_e32 v212, v212, v213
	s_waitcnt vmcnt(8)
;     __device__ __forceinline__ void operator()(const f32x4 (&acc)[2][2][4][2], const Unit& u, int wr, int wc, int fr, int fq) const {
;     ...
;             for (int mm = 0; mm < 2; ++mm) { const int m = 2 * mp + mm; float s = 0.f;
; #pragma unroll
;                 for (int bj = 0; bj < 2; ++bj)
; #pragma unroll
;                     for (int n = 0; n < 2; ++n) { const f32x4 x = bb[mm][bj][n] + gt[bj][n] * acc[ai][bj][m][n]; s += (x[0] * x[0] + x[1] * x[1]) + (x[2] * x[2] + x[3] * x[3]); }
;                 s += __shfl_xor(s, 16); s += __shfl_xor(s, 32);
;                 if (fq == 0) P[(ai * HALF + wr * 64 + m * 16 + fr) * 4 + wc] = s; }
;             asm volatile("" ::: "memory"); }
;         asm volatile("s_waitcnt lgkmcnt(0)" ::: "memory"); __builtin_amdgcn_s_barrier(); asm volatile("" ::: "memory");
	v_lshlrev_b32_e32 v146, 16, v220
	v_and_b32_e32 v147, 0xffff0000, v220
	v_lshlrev_b32_e32 v220, 16, v221
	v_and_b32_e32 v221, 0xffff0000, v221
	v_pk_fma_f32 v[54:55], v[54:55], v[142:143], v[146:147]
	v_pk_fma_f32 v[56:57], v[56:57], v[144:145], v[220:221]
	v_pk_mul_f32 v[220:221], v[54:55], v[54:55]
	v_pk_fma_f32 v[220:221], v[56:57], v[56:57], v[220:221]
	v_lshlrev_b32_e32 v146, 16, v222
	v_and_b32_e32 v147, 0xffff0000, v222
	v_lshlrev_b32_e32 v222, 16, v223
	v_and_b32_e32 v223, 0xffff0000, v223
	v_pk_fma_f32 v[50:51], v[50:51], v[138:139], v[146:147]
	v_pk_fma_f32 v[52:53], v[52:53], v[140:141], v[222:223]
	v_pk_fma_f32 v[220:221], v[50:51], v[50:51], v[220:221]
	v_pk_fma_f32 v[220:221], v[52:53], v[52:53], v[220:221]
	v_lshlrev_b32_e32 v146, 16, v226
	v_and_b32_e32 v147, 0xffff0000, v226
	v_lshlrev_b32_e32 v226, 16, v227
	v_and_b32_e32 v227, 0xffff0000, v227
	v_pk_fma_f32 v[30:31], v[30:31], v[134:135], v[146:147]
	v_pk_fma_f32 v[32:33], v[32:33], v[136:137], v[226:227]
	v_pk_fma_f32 v[220:221], v[30:31], v[30:31], v[220:221]
	v_pk_fma_f32 v[220:221], v[32:33], v[32:33], v[220:221]
	v_lshlrev_b32_e32 v146, 16, v228
	v_and_b32_e32 v147, 0xffff0000, v228
	v_lshlrev_b32_e32 v228, 16, v229
	v_and_b32_e32 v229, 0xffff0000, v229
	v_pk_fma_f32 v[22:23], v[22:23], v[130:131], v[146:147]
	v_pk_fma_f32 v[24:25], v[24:25], v[132:133], v[228:229]
	v_pk_fma_f32 v[220:221], v[22:23], v[22:23], v[220:221]
	v_pk_fma_f32 v[220:221], v[24:25], v[24:25], v[220:221]
	v_add_f32_e32 v220, v220, v221
	s_waitcnt vmcnt(4)
	v_lshlrev_b32_e32 v146, 16, v230
	v_and_b32_e32 v147, 0xffff0000, v230
	v_lshlrev_b32_e32 v230, 16, v231
	v_and_b32_e32 v231, 0xffff0000, v231
	v_pk_fma_f32 v[42:43], v[42:43], v[142:143], v[146:147]
	v_pk_fma_f32 v[44:45], v[44:45], v[144:145], v[230:231]
	v_pk_mul_f32 v[230:231], v[42:43], v[42:43]
	v_pk_fma_f32 v[230:231], v[44:45], v[44:45], v[230:231]
	v_lshlrev_b32_e32 v146, 16, v232
	v_and_b32_e32 v147, 0xffff0000, v232
	v_lshlrev_b32_e32 v232, 16, v233
	v_and_b32_e32 v233, 0xffff0000, v233
	v_pk_fma_f32 v[34:35], v[34:35], v[138:139], v[146:147]
	v_pk_fma_f32 v[36:37], v[36:37], v[140:141], v[232:233]
	v_pk_fma_f32 v[230:231], v[34:35], v[34:35], v[230:231]
	v_pk_fma_f32 v[230:231], v[36:37], v[36:37], v[230:231]
	v_lshlrev_b32_e32 v146, 16, v234
	v_and_b32_e32 v147, 0xffff0000, v234
	v_lshlrev_b32_e32 v234, 16, v235
	v_and_b32_e32 v235, 0xffff0000, v235
	v_pk_fma_f32 v[14:15], v[14:15], v[134:135], v[146:147]
	v_pk_fma_f32 v[16:17], v[16:17], v[136:137], v[234:235]
	v_pk_fma_f32 v[230:231], v[14:15], v[14:15], v[230:231]
	v_pk_fma_f32 v[230:231], v[16:17], v[16:17], v[230:231]
	v_lshlrev_b32_e32 v146, 16, v238
	v_and_b32_e32 v147, 0xffff0000, v238
	v_lshlrev_b32_e32 v238, 16, v239
	v_and_b32_e32 v239, 0xffff0000, v239
	v_pk_fma_f32 v[10:11], v[10:11], v[130:131], v[146:147]
	v_pk_fma_f32 v[12:13], v[12:13], v[132:133], v[238:239]
	v_pk_fma_f32 v[230:231], v[10:11], v[10:11], v[230:231]
	v_pk_fma_f32 v[230:231], v[12:13], v[12:13], v[230:231]
	v_add_f32_e32 v230, v230, v231
	s_waitcnt vmcnt(0)
	v_lshlrev_b32_e32 v146, 16, v240
	v_and_b32_e32 v147, 0xffff0000, v240
	v_lshlrev_b32_e32 v240, 16, v241
	v_and_b32_e32 v241, 0xffff0000, v241
	v_pk_fma_f32 v[26:27], v[26:27], v[142:143], v[146:147]
	v_pk_fma_f32 v[28:29], v[28:29], v[144:145], v[240:241]
	v_pk_mul_f32 v[240:241], v[26:27], v[26:27]
	v_pk_fma_f32 v[240:241], v[28:29], v[28:29], v[240:241]
	v_lshlrev_b32_e32 v146, 16, v242
	v_and_b32_e32 v147, 0xffff0000, v242
	v_lshlrev_b32_e32 v242, 16, v243
	v_and_b32_e32 v243, 0xffff0000, v243
	v_pk_fma_f32 v[18:19], v[18:19], v[138:139], v[146:147]
	v_pk_fma_f32 v[20:21], v[20:21], v[140:141], v[242:243]
	v_pk_fma_f32 v[240:241], v[18:19], v[18:19], v[240:241]
	v_pk_fma_f32 v[240:241], v[20:21], v[20:21], v[240:241]
	v_lshlrev_b32_e32 v146, 16, v244
	v_and_b32_e32 v147, 0xffff0000, v244
	v_lshlrev_b32_e32 v244, 16, v245
	v_and_b32_e32 v245, 0xffff0000, v245
	v_pk_fma_f32 v[6:7], v[6:7], v[134:135], v[146:147]
	v_pk_fma_f32 v[8:9], v[8:9], v[136:137], v[244:245]
	v_pk_fma_f32 v[240:241], v[6:7], v[6:7], v[240:241]
	v_pk_fma_f32 v[240:241], v[8:9], v[8:9], v[240:241]
	v_lshlrev_b32_e32 v146, 16, v246
	v_and_b32_e32 v147, 0xffff0000, v246
	v_lshlrev_b32_e32 v246, 16, v247
	v_and_b32_e32 v247, 0xffff0000, v247
	v_pk_fma_f32 v[2:3], v[2:3], v[130:131], v[146:147]
	v_pk_fma_f32 v[4:5], v[4:5], v[132:133], v[246:247]
	v_pk_fma_f32 v[240:241], v[2:3], v[2:3], v[240:241]
	v_pk_fma_f32 v[240:241], v[4:5], v[4:5], v[240:241]
	v_add_f32_e32 v240, v240, v241
	ds_bpermute_b32 v152, v157, v150
	ds_bpermute_b32 v178, v157, v160
	ds_bpermute_b32 v196, v157, v194
	ds_bpermute_b32 v204, v157, v202
	ds_bpermute_b32 v214, v157, v212
	ds_bpermute_b32 v222, v157, v220
	ds_bpermute_b32 v232, v157, v230
	ds_bpermute_b32 v242, v157, v240
	s_waitcnt lgkmcnt(0)
	v_add_f32_e32 v150, v150, v152
	v_add_f32_e32 v160, v160, v178
	v_add_f32_e32 v194, v194, v196
	v_add_f32_e32 v202, v202, v204
	v_add_f32_e32 v212, v212, v214
	v_add_f32_e32 v220, v220, v222
	v_add_f32_e32 v230, v230, v232
	v_add_f32_e32 v240, v240, v242
	ds_bpermute_b32 v152, v175, v150
	ds_bpermute_b32 v178, v175, v160
	ds_bpermute_b32 v196, v175, v194
	ds_bpermute_b32 v204, v175, v202
	ds_bpermute_b32 v214, v175, v212
	ds_bpermute_b32 v222, v175, v220
	ds_bpermute_b32 v232, v175, v230
	ds_bpermute_b32 v242, v175, v240
	s_waitcnt lgkmcnt(0)
	v_add_f32_e32 v150, v150, v152
	v_add_f32_e32 v160, v160, v178
	v_add_f32_e32 v194, v194, v196
	v_add_f32_e32 v202, v202, v204
	v_add_f32_e32 v212, v212, v214
	v_add_f32_e32 v220, v220, v222
	v_add_f32_e32 v230, v230, v232
	v_add_f32_e32 v240, v240, v242
	s_and_saveexec_b64 s[70:71], s[12:13]
	ds_write_b32 v182, v150
	ds_write_b32 v182, v160 offset:256
	ds_write_b32 v182, v194 offset:512
	ds_write_b32 v182, v202 offset:768
	ds_write_b32 v182, v212 offset:2048
	ds_write_b32 v182, v220 offset:2304
	ds_write_b32 v182, v230 offset:2560
	ds_write_b32 v182, v240 offset:2816
	s_or_b64 exec, exec, s[70:71]
	v_and_b32_e32 v146, -16, v156
	s_waitcnt lgkmcnt(0)
	v_or_b32_e32 v147, s34, v190
	s_waitcnt lgkmcnt(0)
	s_barrier
; #define PG8_LAS __attribute__((address_space(3)))
;     __device__ __forceinline__ void operator()(const f32x4 (&acc)[2][2][4][2], const Unit& u, int wr, int wc, int fr, int fq) const {
;     ...
;         const int tid = (wr * 4 + wc) * 64 + fq * 16 + fr;
;         if (tid < 256) { const f32x4 p = *(const PG8_LAS f32x4*)(P + tid * 4); __hip_atomic_store(ssq + (size_t)(u.pm * BM + tid) * 4 + u.pn, (p[0] + p[1]) + (p[2] + p[3]), __ATOMIC_RELAXED, __HIP_MEMORY_SCOPE_AGENT); }
;     ...
;             for (int n = 0; n < 2; ++n) { c1[bj][n] = *(const f32x4*)(g + col0b + bj * HALF + n * 16);
	v_lshlrev_b64 v[148:149], 2, v[176:177]
	v_lshl_add_u64 v[148:149], s[20:21], 0, v[148:149]
	global_load_dwordx4 v[130:133], v[148:149], off
	global_load_dwordx4 v[134:137], v[148:149], off offset:64
	global_load_dwordx4 v[138:141], v[148:149], off offset:512
	global_load_dwordx4 v[142:145], v[148:149], off offset:576
	v_add_u32_e32 v148, v147, v146
	s_movk_i32 s8, 0x100
	v_add_u32_e32 v146, s41, v148
	v_cmp_gt_i32_e64 s[12:13], s8, v148
	v_ashrrev_i32_e32 v147, 31, v146
	s_and_saveexec_b64 s[70:71], s[12:13]
	s_cbranch_execz .LBB0_1621
	v_lshl_add_u32 v149, v148, 4, 0
	v_add_u32_e32 v149, 0x20400, v149
	ds_read_b128 v[150:153], v149
	v_lshl_add_u64 v[154:155], v[146:147], 4, s[44:45]
	s_ashr_i32 s69, s68, 31
	v_lshl_add_u64 v[154:155], s[68:69], 2, v[154:155]
	s_waitcnt lgkmcnt(0)
	v_mov_b32_e32 v156, v151
	v_mov_b32_e32 v157, v152
	v_mov_b32_e32 v151, v153
	v_pk_add_f32 v[150:151], v[156:157], v[150:151]
	s_nop 0
	v_pk_add_f32 v[150:151], v[150:151], v[150:151] op_sel:[0,1] op_sel_hi:[1,0]
	global_store_dword v[154:155], v150, off sc1

;     __device__ __forceinline__ void operator()(const f32x4 (&acc)[2][2][4][2], const Unit& u, int wr, int wc, int fr, int fq) const {
;     ...
;         asm volatile("s_waitcnt lgkmcnt(0)" ::: "memory"); __builtin_amdgcn_s_barrier(); asm volatile("" ::: "memory");
;         int row0b = row0, col0b = col0; asm volatile("" : "+v"(row0b), "+v"(col0b));
;         f32x4 c1[2][2], c2[2][2];
; #pragma unroll
;         for (int bj = 0; bj < 2; ++bj)
; #pragma unroll
;             for (int n = 0; n < 2; ++n) { c1[bj][n] = *(const f32x4*)(g + col0b + bj * HALF + n * 16);
;                 if (MODE == 0) { const float* mr = mod + (size_t)((u.pm * BM) >> 11) * NMOD + col0b + bj * HALF + n * 16; c1[bj][n] = c1[bj][n] * (*(const f32x4*)(mr + 4096) + 1.f); c2[bj][n] = *(const f32x4*)(mr + 3072); } }
.LBB0_1643:
	s_or_b64 exec, exec, s[14:15]
	v_mov_b32_e32 v146, v176
	v_mov_b32_e32 v148, v174
	s_waitcnt lgkmcnt(0)
	s_barrier
	v_lshl_add_u32 v175, v183, 2, s84
	ds_read_b32 v192, v175 offset:4096
	ds_read_b32 v194, v175 offset:4160
	ds_read_b32 v196, v175 offset:4224
	ds_read_b32 v198, v175 offset:4288
	ds_read_b32 v200, v175 offset:4608
	ds_read_b32 v202, v175 offset:4672
	ds_read_b32 v204, v175 offset:4736
	ds_read_b32 v206, v175 offset:4800
	v_lshlrev_b64 v[178:179], 2, v[176:177]
	v_lshl_add_u64 v[146:147], s[20:21], 0, v[178:179]
	s_nop 0
	v_add_u32_e32 v182, s41, v183
	v_ashrrev_i32_e32 v183, 31, v182
	v_lshlrev_b64 v[180:181], 12, v[182:183]
	v_lshl_add_u64 v[180:181], s[18:19], 0, v[180:181]
	v_lshl_add_u64 v[180:181], v[180:181], 0, v[178:179]
	s_mov_b64 s[24:25], 0x10000
	s_mov_b64 s[14:15], 0x50000
	s_waitcnt vmcnt(0) lgkmcnt(0)
	v_pk_mul_f32 v[210:211], v[126:127], v[192:193] op_sel_hi:[1,0]
	v_pk_mul_f32 v[212:213], v[128:129], v[192:193] op_sel_hi:[1,0]
	v_pk_mul_f32 v[210:211], v[210:211], v[130:131]
	v_pk_mul_f32 v[212:213], v[212:213], v[132:133]
	global_store_dwordx4 v[180:181], v[210:213], off
	v_pk_mul_f32 v[214:215], v[122:123], v[192:193] op_sel_hi:[1,0]
	v_pk_mul_f32 v[216:217], v[124:125], v[192:193] op_sel_hi:[1,0]
	v_pk_mul_f32 v[214:215], v[214:215], v[134:135]
	v_pk_mul_f32 v[216:217], v[216:217], v[136:137]
	global_store_dwordx4 v[180:181], v[214:217], off offset:64
	v_pk_mul_f32 v[218:219], v[110:111], v[192:193] op_sel_hi:[1,0]
	v_pk_mul_f32 v[220:221], v[112:113], v[192:193] op_sel_hi:[1,0]
	v_pk_mul_f32 v[218:219], v[218:219], v[138:139]
	v_pk_mul_f32 v[220:221], v[220:221], v[140:141]
	global_store_dwordx4 v[180:181], v[218:221], off offset:512
	v_pk_mul_f32 v[226:227], v[102:103], v[192:193] op_sel_hi:[1,0]
	v_pk_mul_f32 v[228:229], v[104:105], v[192:193] op_sel_hi:[1,0]
	v_pk_mul_f32 v[226:227], v[226:227], v[142:143]
	v_pk_mul_f32 v[228:229], v[228:229], v[144:145]
	global_store_dwordx4 v[180:181], v[226:229], off offset:576
	v_lshl_add_u64 v[180:181], v[180:181], 0, s[24:25]
	v_pk_mul_f32 v[230:231], v[118:119], v[194:195] op_sel_hi:[1,0]
	v_pk_mul_f32 v[232:233], v[120:121], v[194:195] op_sel_hi:[1,0]
	v_pk_mul_f32 v[230:231], v[230:231], v[130:131]
	v_pk_mul_f32 v[232:233], v[232:233], v[132:133]
	global_store_dwordx4 v[180:181], v[230:233], off
	v_pk_mul_f32 v[238:239], v[114:115], v[194:195] op_sel_hi:[1,0]
	v_pk_mul_f32 v[240:241], v[116:117], v[194:195] op_sel_hi:[1,0]
	v_pk_mul_f32 v[238:239], v[238:239], v[134:135]
	v_pk_mul_f32 v[240:241], v[240:241], v[136:137]
	global_store_dwordx4 v[180:181], v[238:241], off offset:64
	v_pk_mul_f32 v[242:243], v[94:95], v[194:195] op_sel_hi:[1,0]
	v_pk_mul_f32 v[244:245], v[96:97], v[194:195] op_sel_hi:[1,0]
	v_pk_mul_f32 v[242:243], v[242:243], v[138:139]
	v_pk_mul_f32 v[244:245], v[244:245], v[140:141]
	global_store_dwordx4 v[180:181], v[242:245], off offset:512
	v_pk_mul_f32 v[246:247], v[86:87], v[194:195] op_sel_hi:[1,0]
	v_pk_mul_f32 v[248:249], v[88:89], v[194:195] op_sel_hi:[1,0]
	v_pk_mul_f32 v[246:247], v[246:247], v[142:143]
	v_pk_mul_f32 v[248:249], v[248:249], v[144:145]
	global_store_dwordx4 v[180:181], v[246:249], off offset:576
	v_lshl_add_u64 v[180:181], v[180:181], 0, s[24:25]
	v_pk_mul_f32 v[210:211], v[106:107], v[196:197] op_sel_hi:[1,0]
	v_pk_mul_f32 v[212:213], v[108:109], v[196:197] op_sel_hi:[1,0]
	v_pk_mul_f32 v[210:211], v[210:211], v[130:131]
	v_pk_mul_f32 v[212:213], v[212:213], v[132:133]
	global_store_dwordx4 v[180:181], v[210:213], off
	v_pk_mul_f32 v[214:215], v[98:99], v[196:197] op_sel_hi:[1,0]
	v_pk_mul_f32 v[216:217], v[100:101], v[196:197] op_sel_hi:[1,0]
	v_pk_mul_f32 v[214:215], v[214:215], v[134:135]
	v_pk_mul_f32 v[216:217], v[216:217], v[136:137]
	global_store_dwordx4 v[180:181], v[214:217], off offset:64
	v_pk_mul_f32 v[218:219], v[78:79], v[196:197] op_sel_hi:[1,0]
	v_pk_mul_f32 v[220:221], v[80:81], v[196:197] op_sel_hi:[1,0]
	v_pk_mul_f32 v[218:219], v[218:219], v[138:139]
	v_pk_mul_f32 v[220:221], v[220:221], v[140:141]
	global_store_dwordx4 v[180:181], v[218:221], off offset:512
	v_pk_mul_f32 v[226:227], v[74:75], v[196:197] op_sel_hi:[1,0]
	v_pk_mul_f32 v[228:229], v[76:77], v[196:197] op_sel_hi:[1,0]
	v_pk_mul_f32 v[226:227], v[226:227], v[142:143]
	v_pk_mul_f32 v[228:229], v[228:229], v[144:145]
	global_store_dwordx4 v[180:181], v[226:229], off offset:576
	v_lshl_add_u64 v[180:181], v[180:181], 0, s[24:25]
	v_pk_mul_f32 v[230:231], v[90:91], v[198:199] op_sel_hi:[1,0]
	v_pk_mul_f32 v[232:233], v[92:93], v[198:199] op_sel_hi:[1,0]
	v_pk_mul_f32 v[230:231], v[230:231], v[130:131]
	v_pk_mul_f32 v[232:233], v[232:233], v[132:133]
	global_store_dwordx4 v[180:181], v[230:233], off
	v_pk_mul_f32 v[238:239], v[82:83], v[198:199] op_sel_hi:[1,0]
	v_pk_mul_f32 v[240:241], v[84:85], v[198:199] op_sel_hi:[1,0]
	v_pk_mul_f32 v[238:239], v[238:239], v[134:135]
	v_pk_mul_f32 v[240:241], v[240:241], v[136:137]
	global_store_dwordx4 v[180:181], v[238:241], off offset:64
	v_pk_mul_f32 v[242:243], v[70:71], v[198:199] op_sel_hi:[1,0]
	v_pk_mul_f32 v[244:245], v[72:73], v[198:199] op_sel_hi:[1,0]
	v_pk_mul_f32 v[242:243], v[242:243], v[138:139]
	v_pk_mul_f32 v[244:245], v[244:245], v[140:141]
	global_store_dwordx4 v[180:181], v[242:245], off offset:512
	v_pk_mul_f32 v[246:247], v[66:67], v[198:199] op_sel_hi:[1,0]
	v_pk_mul_f32 v[248:249], v[68:69], v[198:199] op_sel_hi:[1,0]
	v_pk_mul_f32 v[246:247], v[246:247], v[142:143]
	v_pk_mul_f32 v[248:249], v[248:249], v[144:145]
	global_store_dwordx4 v[180:181], v[246:249], off offset:576
	v_lshl_add_u64 v[180:181], v[180:181], 0, s[14:15]
	v_pk_mul_f32 v[210:211], v[62:63], v[200:201] op_sel_hi:[1,0]
	v_pk_mul_f32 v[212:213], v[64:65], v[200:201] op_sel_hi:[1,0]
	v_pk_mul_f32 v[210:211], v[210:211], v[130:131]
	v_pk_mul_f32 v[212:213], v[212:213], v[132:133]
	global_store_dwordx4 v[180:181], v[210:213], off
	v_pk_mul_f32 v[214:215], v[58:59], v[200:201] op_sel_hi:[1,0]
	v_pk_mul_f32 v[216:217], v[60:61], v[200:201] op_sel_hi:[1,0]
	v_pk_mul_f32 v[214:215], v[214:215], v[134:135]
	v_pk_mul_f32 v[216:217], v[216:217], v[136:137]
	global_store_dwordx4 v[180:181], v[214:217], off offset:64
	v_pk_mul_f32 v[218:219], v[46:47], v[200:201] op_sel_hi:[1,0]
	v_pk_mul_f32 v[220:221], v[48:49], v[200:201] op_sel_hi:[1,0]
	v_pk_mul_f32 v[218:219], v[218:219], v[138:139]
	v_pk_mul_f32 v[220:221], v[220:221], v[140:141]
	global_store_dwordx4 v[180:181], v[218:221], off offset:512
	v_pk_mul_f32 v[226:227], v[38:39], v[200:201] op_sel_hi:[1,0]
	v_pk_mul_f32 v[228:229], v[40:41], v[200:201] op_sel_hi:[1,0]
	v_pk_mul_f32 v[226:227], v[226:227], v[142:143]
	v_pk_mul_f32 v[228:229], v[228:229], v[144:145]
	global_store_dwordx4 v[180:181], v[226:229], off offset:576
	v_lshl_add_u64 v[180:181], v[180:181], 0, s[24:25]
	v_pk_mul_f32 v[230:231], v[54:55], v[202:203] op_sel_hi:[1,0]
	v_pk_mul_f32 v[232:233], v[56:57], v[202:203] op_sel_hi:[1,0]
	v_pk_mul_f32 v[230:231], v[230:231], v[130:131]
	v_pk_mul_f32 v[232:233], v[232:233], v[132:133]
	global_store_dwordx4 v[180:181], v[230:233], off
	v_pk_mul_f32 v[238:239], v[50:51], v[202:203] op_sel_hi:[1,0]
	v_pk_mul_f32 v[240:241], v[52:53], v[202:203] op_sel_hi:[1,0]
	v_pk_mul_f32 v[238:239], v[238:239], v[134:135]
	v_pk_mul_f32 v[240:241], v[240:241], v[136:137]
	global_store_dwordx4 v[180:181], v[238:241], off offset:64
	v_pk_mul_f32 v[242:243], v[30:31], v[202:203] op_sel_hi:[1,0]
	v_pk_mul_f32 v[244:245], v[32:33], v[202:203] op_sel_hi:[1,0]
	v_pk_mul_f32 v[242:243], v[242:243], v[138:139]
	v_pk_mul_f32 v[244:245], v[244:245], v[140:141]
	global_store_dwordx4 v[180:181], v[242:245], off offset:512
	v_pk_mul_f32 v[246:247], v[22:23], v[202:203] op_sel_hi:[1,0]
	v_pk_mul_f32 v[248:249], v[24:25], v[202:203] op_sel_hi:[1,0]
	v_pk_mul_f32 v[246:247], v[246:247], v[142:143]
	v_pk_mul_f32 v[248:249], v[248:249], v[144:145]
	global_store_dwordx4 v[180:181], v[246:249], off offset:576
	v_lshl_add_u64 v[180:181], v[180:181], 0, s[24:25]
	v_pk_mul_f32 v[210:211], v[42:43], v[204:205] op_sel_hi:[1,0]
	v_pk_mul_f32 v[212:213], v[44:45], v[204:205] op_sel_hi:[1,0]
	v_pk_mul_f32 v[210:211], v[210:211], v[130:131]
	v_pk_mul_f32 v[212:213], v[212:213], v[132:133]
	global_store_dwordx4 v[180:181], v[210:213], off
	v_pk_mul_f32 v[214:215], v[34:35], v[204:205] op_sel_hi:[1,0]
	v_pk_mul_f32 v[216:217], v[36:37], v[204:205] op_sel_hi:[1,0]
	v_pk_mul_f32 v[214:215], v[214:215], v[134:135]
	v_pk_mul_f32 v[216:217], v[216:217], v[136:137]
	global_store_dwordx4 v[180:181], v[214:217], off offset:64
	v_pk_mul_f32 v[218:219], v[14:15], v[204:205] op_sel_hi:[1,0]
	v_pk_mul_f32 v[220:221], v[16:17], v[204:205] op_sel_hi:[1,0]
	v_pk_mul_f32 v[218:219], v[218:219], v[138:139]
	v_pk_mul_f32 v[220:221], v[220:221], v[140:141]
	global_store_dwordx4 v[180:181], v[218:221], off offset:512
	v_pk_mul_f32 v[226:227], v[10:11], v[204:205] op_sel_hi:[1,0]
	v_pk_mul_f32 v[228:229], v[12:13], v[204:205] op_sel_hi:[1,0]
	v_pk_mul_f32 v[226:227], v[226:227], v[142:143]
	v_pk_mul_f32 v[228:229], v[228:229], v[144:145]
	global_store_dwordx4 v[180:181], v[226:229], off offset:576
	v_lshl_add_u64 v[180:181], v[180:181], 0, s[24:25]
	v_pk_mul_f32 v[230:231], v[26:27], v[206:207] op_sel_hi:[1,0]
	v_pk_mul_f32 v[232:233], v[28:29], v[206:207] op_sel_hi:[1,0]
	v_pk_mul_f32 v[230:231], v[230:231], v[130:131]
	v_pk_mul_f32 v[232:233], v[232:233], v[132:133]
	global_store_dwordx4 v[180:181], v[230:233], off
	v_pk_mul_f32 v[238:239], v[18:19], v[206:207] op_sel_hi:[1,0]
	v_pk_mul_f32 v[240:241], v[20:21], v[206:207] op_sel_hi:[1,0]
	v_pk_mul_f32 v[238:239], v[238:239], v[134:135]
	v_pk_mul_f32 v[240:241], v[240:241], v[136:137]
	global_store_dwordx4 v[180:181], v[238:241], off offset:64
	v_pk_mul_f32 v[242:243], v[6:7], v[206:207] op_sel_hi:[1,0]
	v_pk_mul_f32 v[244:245], v[8:9], v[206:207] op_sel_hi:[1,0]
	v_pk_mul_f32 v[242:243], v[242:243], v[138:139]
	v_pk_mul_f32 v[244:245], v[244:245], v[140:141]
	global_store_dwordx4 v[180:181], v[242:245], off offset:512
	v_pk_mul_f32 v[246:247], v[2:3], v[206:207] op_sel_hi:[1,0]
	v_pk_mul_f32 v[248:249], v[4:5], v[206:207] op_sel_hi:[1,0]
	v_pk_mul_f32 v[246:247], v[246:247], v[142:143]
	v_pk_mul_f32 v[248:249], v[248:249], v[144:145]
	global_store_dwordx4 v[180:181], v[246:249], off offset:576
	s_mov_b64 s[12:13], 0
